# DSA select bisection: ballot+scalar popcount instead of per-lane counts + DPP reduce
# baseline (speedup 1.0000x reference)
; __device__ __forceinline__ unsigned wave_sum_u32(unsigned c) {
;     c += (unsigned)__builtin_amdgcn_update_dpp(0, (int)c, 0x128, 0xf, 0xf, false);
;     c += (unsigned)__builtin_amdgcn_update_dpp(0, (int)c, 0x124, 0xf, 0xf, false);
;     c += (unsigned)__builtin_amdgcn_update_dpp(0, (int)c, 0x122, 0xf, 0xf, false);
;     c += (unsigned)__builtin_amdgcn_update_dpp(0, (int)c, 0x121, 0xf, 0xf, false);
;     { const auto r = __builtin_amdgcn_permlane16_swap(c, c, false, false); c = r[0] + r[1]; }
;     { const auto r = __builtin_amdgcn_permlane32_swap(c, c, false, false); c = r[0] + r[1]; }
;     return c;
; }
; template <int NJ>
; __device__ __forceinline__ void dsa_select(LAS unsigned char* lds, int qs, int t, int lane) {
;     ...
;     if (t + 1 > 256) {
;         need = 256; theta = 0u;
;     ...
; #pragma unroll
;             for (int j = 0; j < NJ; ++j) c += (v[j] >= tr) ? 1u : 0u;
;             c = wave_sum_u32(c);
;             theta = (c >= 256u) ? tr : theta; }
;         theta = (unsigned)__builtin_amdgcn_readfirstlane((int)theta);
;     }
.LBB0_685:
	s_mov_b32 s98, 15
	s_mov_b32 s17, 0
.Lbis_686:
	s_lshl_b32 s2, 1, s98
	s_or_b32 s2, s2, s17
	v_mov_b32_e32 v98, s2
	s_mov_b32 s99, 0
	v_cmp_ge_u32_e32 vcc, v65, v98
	v_cmp_ge_u32_e64 s[100:101], v66, v98
	s_bcnt1_i32_b64 s0, vcc
	s_add_i32 s99, s99, s0
	v_cmp_ge_u32_e32 vcc, v67, v98
	s_bcnt1_i32_b64 s0, s[100:101]
	s_add_i32 s99, s99, s0
	v_cmp_ge_u32_e64 s[100:101], v68, v98
	s_bcnt1_i32_b64 s0, vcc
	s_add_i32 s99, s99, s0
	v_cmp_ge_u32_e32 vcc, v69, v98
	s_bcnt1_i32_b64 s0, s[100:101]
	s_add_i32 s99, s99, s0
	v_cmp_ge_u32_e64 s[100:101], v70, v98
	s_bcnt1_i32_b64 s0, vcc
	s_add_i32 s99, s99, s0
	v_cmp_ge_u32_e32 vcc, v71, v98
	s_bcnt1_i32_b64 s0, s[100:101]
	s_add_i32 s99, s99, s0
	v_cmp_ge_u32_e64 s[100:101], v72, v98
	s_bcnt1_i32_b64 s0, vcc
	s_add_i32 s99, s99, s0
	v_cmp_ge_u32_e32 vcc, v73, v98
	s_bcnt1_i32_b64 s0, s[100:101]
	s_add_i32 s99, s99, s0
	v_cmp_ge_u32_e64 s[100:101], v74, v98
	s_bcnt1_i32_b64 s0, vcc
	s_add_i32 s99, s99, s0
	v_cmp_ge_u32_e32 vcc, v75, v98
	s_bcnt1_i32_b64 s0, s[100:101]
	s_add_i32 s99, s99, s0
	v_cmp_ge_u32_e64 s[100:101], v76, v98
	s_bcnt1_i32_b64 s0, vcc
	s_add_i32 s99, s99, s0
	v_cmp_ge_u32_e32 vcc, v77, v98
	s_bcnt1_i32_b64 s0, s[100:101]
	s_add_i32 s99, s99, s0
	v_cmp_ge_u32_e64 s[100:101], v78, v98
	s_bcnt1_i32_b64 s0, vcc
	s_add_i32 s99, s99, s0
	v_cmp_ge_u32_e32 vcc, v79, v98
	s_bcnt1_i32_b64 s0, s[100:101]
	s_add_i32 s99, s99, s0
	v_cmp_ge_u32_e64 s[100:101], v80, v98
	s_bcnt1_i32_b64 s0, vcc
	s_add_i32 s99, s99, s0
	v_cmp_ge_u32_e32 vcc, v81, v98
	s_bcnt1_i32_b64 s0, s[100:101]
	s_add_i32 s99, s99, s0
	v_cmp_ge_u32_e64 s[100:101], v82, v98
	s_bcnt1_i32_b64 s0, vcc
	s_add_i32 s99, s99, s0
	v_cmp_ge_u32_e32 vcc, v83, v98
	s_bcnt1_i32_b64 s0, s[100:101]
	s_add_i32 s99, s99, s0
	v_cmp_ge_u32_e64 s[100:101], v84, v98
	s_bcnt1_i32_b64 s0, vcc
	s_add_i32 s99, s99, s0
	v_cmp_ge_u32_e32 vcc, v85, v98
	s_bcnt1_i32_b64 s0, s[100:101]
	s_add_i32 s99, s99, s0
	v_cmp_ge_u32_e64 s[100:101], v86, v98
	s_bcnt1_i32_b64 s0, vcc
	s_add_i32 s99, s99, s0
	v_cmp_ge_u32_e32 vcc, v87, v98
	s_bcnt1_i32_b64 s0, s[100:101]
	s_add_i32 s99, s99, s0
	v_cmp_ge_u32_e64 s[100:101], v88, v98
	s_bcnt1_i32_b64 s0, vcc
	s_add_i32 s99, s99, s0
	v_cmp_ge_u32_e32 vcc, v89, v98
	s_bcnt1_i32_b64 s0, s[100:101]
	s_add_i32 s99, s99, s0
	v_cmp_ge_u32_e64 s[100:101], v90, v98
	s_bcnt1_i32_b64 s0, vcc
	s_add_i32 s99, s99, s0
	v_cmp_ge_u32_e32 vcc, v91, v98
	s_bcnt1_i32_b64 s0, s[100:101]
	s_add_i32 s99, s99, s0
	v_cmp_ge_u32_e64 s[100:101], v92, v98
	s_bcnt1_i32_b64 s0, vcc
	s_add_i32 s99, s99, s0
	v_cmp_ge_u32_e32 vcc, v93, v98
	s_bcnt1_i32_b64 s0, s[100:101]
	s_add_i32 s99, s99, s0
	v_cmp_ge_u32_e64 s[100:101], v94, v98
	s_bcnt1_i32_b64 s0, vcc
	s_add_i32 s99, s99, s0
	v_cmp_ge_u32_e32 vcc, v95, v98
	s_bcnt1_i32_b64 s0, s[100:101]
	s_add_i32 s99, s99, s0
	v_cmp_ge_u32_e64 s[100:101], v96, v98
	s_bcnt1_i32_b64 s0, vcc
	s_add_i32 s99, s99, s0
	s_bcnt1_i32_b64 s0, s[100:101]
	s_add_i32 s99, s99, s0
	s_cmp_gt_u32 s99, 0xff
	s_cselect_b32 s17, s2, s17
	s_add_i32 s98, s98, -1
	s_cmp_lt_i32 s98, 0
	s_cbranch_scc0 .Lbis_686
	s_movk_i32 s2, 0x100
	s_branch .LBB0_693

; __device__ __forceinline__ unsigned wave_sum_u32(unsigned c) {
;     c += (unsigned)__builtin_amdgcn_update_dpp(0, (int)c, 0x128, 0xf, 0xf, false);
;     c += (unsigned)__builtin_amdgcn_update_dpp(0, (int)c, 0x124, 0xf, 0xf, false);
;     c += (unsigned)__builtin_amdgcn_update_dpp(0, (int)c, 0x122, 0xf, 0xf, false);
;     c += (unsigned)__builtin_amdgcn_update_dpp(0, (int)c, 0x121, 0xf, 0xf, false);
;     { const auto r = __builtin_amdgcn_permlane16_swap(c, c, false, false); c = r[0] + r[1]; }
;     { const auto r = __builtin_amdgcn_permlane32_swap(c, c, false, false); c = r[0] + r[1]; }
;     return c;
; }
; template <int NJ>
; __device__ __forceinline__ void dsa_select(LAS unsigned char* lds, int qs, int t, int lane) {
;     ...
;     if (t + 1 > 256) {
;         need = 256; theta = 0u;
;     ...
; #pragma unroll
;             for (int j = 0; j < NJ; ++j) c += (v[j] >= tr) ? 1u : 0u;
;             c = wave_sum_u32(c);
;             theta = (c >= 256u) ? tr : theta; }
;         theta = (unsigned)__builtin_amdgcn_readfirstlane((int)theta);
;     }
.LBB0_877:
	s_mov_b32 s98, 15
	s_mov_b32 s2, 0
.Lbis_878:
	s_lshl_b32 s14, 1, s98
	s_or_b32 s14, s14, s2
	v_mov_b32_e32 v90, s14
	s_mov_b32 s99, 0
	v_cmp_ge_u32_e32 vcc, v65, v90
	v_cmp_ge_u32_e64 s[100:101], v66, v90
	s_bcnt1_i32_b64 s0, vcc
	s_add_i32 s99, s99, s0
	v_cmp_ge_u32_e32 vcc, v67, v90
	s_bcnt1_i32_b64 s0, s[100:101]
	s_add_i32 s99, s99, s0
	v_cmp_ge_u32_e64 s[100:101], v68, v90
	s_bcnt1_i32_b64 s0, vcc
	s_add_i32 s99, s99, s0
	v_cmp_ge_u32_e32 vcc, v69, v90
	s_bcnt1_i32_b64 s0, s[100:101]
	s_add_i32 s99, s99, s0
	v_cmp_ge_u32_e64 s[100:101], v70, v90
	s_bcnt1_i32_b64 s0, vcc
	s_add_i32 s99, s99, s0
	v_cmp_ge_u32_e32 vcc, v71, v90
	s_bcnt1_i32_b64 s0, s[100:101]
	s_add_i32 s99, s99, s0
	v_cmp_ge_u32_e64 s[100:101], v72, v90
	s_bcnt1_i32_b64 s0, vcc
	s_add_i32 s99, s99, s0
	v_cmp_ge_u32_e32 vcc, v73, v90
	s_bcnt1_i32_b64 s0, s[100:101]
	s_add_i32 s99, s99, s0
	v_cmp_ge_u32_e64 s[100:101], v74, v90
	s_bcnt1_i32_b64 s0, vcc
	s_add_i32 s99, s99, s0
	v_cmp_ge_u32_e32 vcc, v75, v90
	s_bcnt1_i32_b64 s0, s[100:101]
	s_add_i32 s99, s99, s0
	v_cmp_ge_u32_e64 s[100:101], v76, v90
	s_bcnt1_i32_b64 s0, vcc
	s_add_i32 s99, s99, s0
	v_cmp_ge_u32_e32 vcc, v77, v90
	s_bcnt1_i32_b64 s0, s[100:101]
	s_add_i32 s99, s99, s0
	v_cmp_ge_u32_e64 s[100:101], v78, v90
	s_bcnt1_i32_b64 s0, vcc
	s_add_i32 s99, s99, s0
	v_cmp_ge_u32_e32 vcc, v79, v90
	s_bcnt1_i32_b64 s0, s[100:101]
	s_add_i32 s99, s99, s0
	v_cmp_ge_u32_e64 s[100:101], v80, v90
	s_bcnt1_i32_b64 s0, vcc
	s_add_i32 s99, s99, s0
	v_cmp_ge_u32_e32 vcc, v81, v90
	s_bcnt1_i32_b64 s0, s[100:101]
	s_add_i32 s99, s99, s0
	v_cmp_ge_u32_e64 s[100:101], v82, v90
	s_bcnt1_i32_b64 s0, vcc
	s_add_i32 s99, s99, s0
	v_cmp_ge_u32_e32 vcc, v83, v90
	s_bcnt1_i32_b64 s0, s[100:101]
	s_add_i32 s99, s99, s0
	v_cmp_ge_u32_e64 s[100:101], v84, v90
	s_bcnt1_i32_b64 s0, vcc
	s_add_i32 s99, s99, s0
	v_cmp_ge_u32_e32 vcc, v85, v90
	s_bcnt1_i32_b64 s0, s[100:101]
	s_add_i32 s99, s99, s0
	v_cmp_ge_u32_e64 s[100:101], v86, v90
	s_bcnt1_i32_b64 s0, vcc
	s_add_i32 s99, s99, s0
	v_cmp_ge_u32_e32 vcc, v87, v90
	s_bcnt1_i32_b64 s0, s[100:101]
	s_add_i32 s99, s99, s0
	v_cmp_ge_u32_e64 s[100:101], v88, v90
	s_bcnt1_i32_b64 s0, vcc
	s_add_i32 s99, s99, s0
	s_bcnt1_i32_b64 s0, s[100:101]
	s_add_i32 s99, s99, s0
	s_cmp_gt_u32 s99, 0xff
	s_cselect_b32 s2, s14, s2
	s_add_i32 s98, s98, -1
	s_cmp_lt_i32 s98, 0
	s_cbranch_scc0 .Lbis_878
	s_movk_i32 s14, 0x100
	s_branch .LBB0_883

; __device__ __forceinline__ unsigned wave_sum_u32(unsigned c) {
;     c += (unsigned)__builtin_amdgcn_update_dpp(0, (int)c, 0x128, 0xf, 0xf, false);
;     c += (unsigned)__builtin_amdgcn_update_dpp(0, (int)c, 0x124, 0xf, 0xf, false);
;     c += (unsigned)__builtin_amdgcn_update_dpp(0, (int)c, 0x122, 0xf, 0xf, false);
;     c += (unsigned)__builtin_amdgcn_update_dpp(0, (int)c, 0x121, 0xf, 0xf, false);
;     { const auto r = __builtin_amdgcn_permlane16_swap(c, c, false, false); c = r[0] + r[1]; }
;     { const auto r = __builtin_amdgcn_permlane32_swap(c, c, false, false); c = r[0] + r[1]; }
;     return c;
; }
; template <int NJ>
; __device__ __forceinline__ void dsa_select(LAS unsigned char* lds, int qs, int t, int lane) {
;     ...
;     if (t + 1 > 256) {
;         need = 256; theta = 0u;
;     ...
; #pragma unroll
;             for (int j = 0; j < NJ; ++j) c += (v[j] >= tr) ? 1u : 0u;
;             c = wave_sum_u32(c);
;             theta = (c >= 256u) ? tr : theta; }
;         theta = (unsigned)__builtin_amdgcn_readfirstlane((int)theta);
;     }
.Lbis_1021:
	s_lshl_b32 s14, 1, s98
	s_or_b32 s14, s14, s2
	v_mov_b32_e32 v83, s14
	s_mov_b32 s99, 0
	v_cmp_ge_u32_e32 vcc, v65, v83
	v_cmp_ge_u32_e64 s[100:101], v66, v83
	s_bcnt1_i32_b64 s0, vcc
	s_add_i32 s99, s99, s0
	v_cmp_ge_u32_e32 vcc, v67, v83
	s_bcnt1_i32_b64 s0, s[100:101]
	s_add_i32 s99, s99, s0
	v_cmp_ge_u32_e64 s[100:101], v68, v83
	s_bcnt1_i32_b64 s0, vcc
	s_add_i32 s99, s99, s0
	v_cmp_ge_u32_e32 vcc, v69, v83
	s_bcnt1_i32_b64 s0, s[100:101]
	s_add_i32 s99, s99, s0
	v_cmp_ge_u32_e64 s[100:101], v70, v83
	s_bcnt1_i32_b64 s0, vcc
	s_add_i32 s99, s99, s0
	v_cmp_ge_u32_e32 vcc, v71, v83
	s_bcnt1_i32_b64 s0, s[100:101]
	s_add_i32 s99, s99, s0
	v_cmp_ge_u32_e64 s[100:101], v72, v83
	s_bcnt1_i32_b64 s0, vcc
	s_add_i32 s99, s99, s0
	v_cmp_ge_u32_e32 vcc, v73, v83
	s_bcnt1_i32_b64 s0, s[100:101]
	s_add_i32 s99, s99, s0
	v_cmp_ge_u32_e64 s[100:101], v74, v83
	s_bcnt1_i32_b64 s0, vcc
	s_add_i32 s99, s99, s0
	v_cmp_ge_u32_e32 vcc, v75, v83
	s_bcnt1_i32_b64 s0, s[100:101]
	s_add_i32 s99, s99, s0
	v_cmp_ge_u32_e64 s[100:101], v76, v83
	s_bcnt1_i32_b64 s0, vcc
	s_add_i32 s99, s99, s0
	v_cmp_ge_u32_e32 vcc, v77, v83
	s_bcnt1_i32_b64 s0, s[100:101]
	s_add_i32 s99, s99, s0
	v_cmp_ge_u32_e64 s[100:101], v78, v83
	s_bcnt1_i32_b64 s0, vcc
	s_add_i32 s99, s99, s0
	v_cmp_ge_u32_e32 vcc, v79, v83
	s_bcnt1_i32_b64 s0, s[100:101]
	s_add_i32 s99, s99, s0
	v_cmp_ge_u32_e64 s[100:101], v80, v83
	s_bcnt1_i32_b64 s0, vcc
	s_add_i32 s99, s99, s0
	s_bcnt1_i32_b64 s0, s[100:101]
	s_add_i32 s99, s99, s0
	s_cmp_gt_u32 s99, 0xff
	s_cselect_b32 s2, s14, s2
	s_add_i32 s98, s98, -1
	s_cmp_lt_i32 s98, 0
	s_cbranch_scc0 .Lbis_1021
	s_movk_i32 s14, 0x100
	s_branch .LBB0_1026

; __device__ __forceinline__ unsigned wave_sum_u32(unsigned c) {
;     c += (unsigned)__builtin_amdgcn_update_dpp(0, (int)c, 0x128, 0xf, 0xf, false);
;     c += (unsigned)__builtin_amdgcn_update_dpp(0, (int)c, 0x124, 0xf, 0xf, false);
;     c += (unsigned)__builtin_amdgcn_update_dpp(0, (int)c, 0x122, 0xf, 0xf, false);
;     c += (unsigned)__builtin_amdgcn_update_dpp(0, (int)c, 0x121, 0xf, 0xf, false);
;     { const auto r = __builtin_amdgcn_permlane16_swap(c, c, false, false); c = r[0] + r[1]; }
;     { const auto r = __builtin_amdgcn_permlane32_swap(c, c, false, false); c = r[0] + r[1]; }
;     return c;
; }
; template <int NJ>
; __device__ __forceinline__ void dsa_select(LAS unsigned char* lds, int qs, int t, int lane) {
;     ...
;     if (t + 1 > 256) {
;         need = 256; theta = 0u;
;     ...
; #pragma unroll
;             for (int j = 0; j < NJ; ++j) c += (v[j] >= tr) ? 1u : 0u;
;             c = wave_sum_u32(c);
;             theta = (c >= 256u) ? tr : theta; }
;         theta = (unsigned)__builtin_amdgcn_readfirstlane((int)theta);
;     }
.Lbis_1117:
	s_lshl_b32 s14, 1, s98
	s_or_b32 s14, s14, s2
	v_mov_b32_e32 v75, s14
	s_mov_b32 s99, 0
	v_cmp_ge_u32_e32 vcc, v65, v75
	v_cmp_ge_u32_e64 s[100:101], v66, v75
	s_bcnt1_i32_b64 s0, vcc
	s_add_i32 s99, s99, s0
	v_cmp_ge_u32_e32 vcc, v67, v75
	s_bcnt1_i32_b64 s0, s[100:101]
	s_add_i32 s99, s99, s0
	v_cmp_ge_u32_e64 s[100:101], v68, v75
	s_bcnt1_i32_b64 s0, vcc
	s_add_i32 s99, s99, s0
	v_cmp_ge_u32_e32 vcc, v69, v75
	s_bcnt1_i32_b64 s0, s[100:101]
	s_add_i32 s99, s99, s0
	v_cmp_ge_u32_e64 s[100:101], v70, v75
	s_bcnt1_i32_b64 s0, vcc
	s_add_i32 s99, s99, s0
	v_cmp_ge_u32_e32 vcc, v71, v75
	s_bcnt1_i32_b64 s0, s[100:101]
	s_add_i32 s99, s99, s0
	v_cmp_ge_u32_e64 s[100:101], v72, v75
	s_bcnt1_i32_b64 s0, vcc
	s_add_i32 s99, s99, s0
	s_bcnt1_i32_b64 s0, s[100:101]
	s_add_i32 s99, s99, s0
	s_cmp_gt_u32 s99, 0xff
	s_cselect_b32 s2, s14, s2
	s_add_i32 s98, s98, -1
	s_cmp_lt_i32 s98, 0
	s_cbranch_scc0 .Lbis_1117
	s_movk_i32 s14, 0x100
	s_branch .LBB0_1122

; #define LAS __attribute__((address_space(3)))
; __global__ void __launch_bounds__(NWAVES * 64, 2) mega(Args a) {
;     extern __shared__ __attribute__((aligned(16))) unsigned char lds_raw[];
;     LAS unsigned char* lds = (LAS unsigned char*)lds_raw;
;     const int wave = __builtin_amdgcn_readfirstlane((int)threadIdx.x >> 6);
;     ...
;     const int G = gridDim.x, bx = blockIdx.x, vcu = (G % 8 == 0) ? (bx % 8) * (G / 8) + bx / 8 : bx;
;     const int gw = vcu * NWAVES + wave, ngw = G * NWAVES, ngt = G * NWAVES * 64;
;     Ptrs p;
;     p.x = a.in[0]; p.pos = (const int*)a.in[1]; p.w_in = a.in[2]; p.sink = a.in[3];  p.w_out = a.in[7];
;     p.f1i = a.in[8]; p.f1o = a.in[9]; p.f2i = a.in[10]; p.f2o = a.in[11]; p.lng = a.in[12]; p.lnb = a.in[13];
;     unsigned char* ws = a.ws;
;     p.Y = a.out; p.stats = (float*)(ws + WS_STATS); p.cosT = (float*)(ws + WS_ROPE); p.sinT = p.cosT + (size_t)T_ * 32; p.ones = (float*)(ws + WS_LNV); p.zeros = p.ones + 1024;
;     p.aux = (float*)(ws + WS_AUX); p.LSE = (float*)(ws + WS_LSE); p.Yb = (bf16_t*)(ws + WS_YB); p.Wb = (bf16_t*)(ws + WS_W); p.BIG = (bf16_t*)(ws + WS_BIG); p.OB = (bf16_t*)(ws + WS_OBUF); p.ACX = (bf16_t*)(ws + WS_ACX);
;     ...
;     cg::grid_group grid = cg::this_grid();
;     if (threadIdx.x < 64) ((LAS unsigned*)(lds + LDS_MISC))[threadIdx.x] = 0u;
;     __syncthreads();
;     XcdBarrier xbar = xcd_barrier_post((unsigned*)(a.ws + WS_CTL), (volatile LAS unsigned*)(lds + LDS_MISC));
	.amdhsa_kernel _Z4mega4Args
		.amdhsa_group_segment_fixed_size 0
		.amdhsa_private_segment_fixed_size 0
		.amdhsa_kernarg_size 392
		.amdhsa_user_sgpr_count 2
		.amdhsa_user_sgpr_dispatch_ptr 0
		.amdhsa_user_sgpr_queue_ptr 0
		.amdhsa_user_sgpr_kernarg_segment_ptr 1
		.amdhsa_user_sgpr_dispatch_id 0
		.amdhsa_user_sgpr_kernarg_preload_length 0
		.amdhsa_user_sgpr_kernarg_preload_offset 0
		.amdhsa_user_sgpr_private_segment_size 0
		.amdhsa_uses_dynamic_stack 0
		.amdhsa_enable_private_segment 0
		.amdhsa_system_sgpr_workgroup_id_x 1
		.amdhsa_system_sgpr_workgroup_id_y 0
		.amdhsa_system_sgpr_workgroup_id_z 0
		.amdhsa_system_sgpr_workgroup_info 0
		.amdhsa_system_vgpr_workitem_id 2
		.amdhsa_next_free_vgpr 256
		.amdhsa_next_free_sgpr 102
		.amdhsa_accum_offset 256
		.amdhsa_reserve_vcc 1
		.amdhsa_float_round_mode_32 0
		.amdhsa_float_round_mode_16_64 0
		.amdhsa_float_denorm_mode_32 3
		.amdhsa_float_denorm_mode_16_64 3
		.amdhsa_dx10_clamp 1
		.amdhsa_ieee_mode 1
		.amdhsa_fp16_overflow 0
		.amdhsa_tg_split 0
		.amdhsa_exception_fp_ieee_invalid_op 0
		.amdhsa_exception_fp_denorm_src 0
		.amdhsa_exception_fp_ieee_div_zero 0
		.amdhsa_exception_fp_ieee_overflow 0
		.amdhsa_exception_fp_ieee_underflow 0
		.amdhsa_exception_fp_ieee_inexact 0
		.amdhsa_exception_int_div_zero 0
	.end_amdhsa_kernel

; __global__ void __launch_bounds__(NWAVES * 64, 2) mega(Args a) {
amdhsa.kernels:
  - .agpr_count:     0
    .args:
      - .offset:         0
        .size:           136
        .value_kind:     by_value
      - .offset:         136
        .size:           4
        .value_kind:     hidden_block_count_x
      - .offset:         140
        .size:           4
        .value_kind:     hidden_block_count_y
      - .offset:         144
        .size:           4
        .value_kind:     hidden_block_count_z
      - .offset:         148
        .size:           2
        .value_kind:     hidden_group_size_x
      - .offset:         150
        .size:           2
        .value_kind:     hidden_group_size_y
      - .offset:         152
        .size:           2
        .value_kind:     hidden_group_size_z
      - .offset:         154
        .size:           2
        .value_kind:     hidden_remainder_x
      - .offset:         156
        .size:           2
        .value_kind:     hidden_remainder_y
      - .offset:         158
        .size:           2
        .value_kind:     hidden_remainder_z
      - .offset:         176
        .size:           8
        .value_kind:     hidden_global_offset_x
      - .offset:         184
        .size:           8
        .value_kind:     hidden_global_offset_y
      - .offset:         192
        .size:           8
        .value_kind:     hidden_global_offset_z
      - .offset:         200
        .size:           2
        .value_kind:     hidden_grid_dims
      - .offset:         224
        .size:           8
        .value_kind:     hidden_multigrid_sync_arg
      - .offset:         256
        .size:           4
        .value_kind:     hidden_dynamic_lds_size
    .group_segment_fixed_size: 0
    .kernarg_segment_align: 8
    .kernarg_segment_size: 392
    .language:       OpenCL C
    .language_version:
      - 2
      - 0
    .max_flat_workgroup_size: 512
    .name:           _Z4mega4Args
    .private_segment_fixed_size: 0
    .sgpr_count:     108
    .sgpr_spill_count: 380
    .symbol:         _Z4mega4Args.kd
    .uniform_work_group_size: 1
    .uses_dynamic_stack: false
    .vgpr_count:     256
    .vgpr_spill_count: 0
    .wavefront_size: 64
